# attention: 3 LDS stages, per-tile barrier moved mid-stream (no barrier at tile boundary)
# speedup vs baseline: 1.0160x; 1.0044x over previous
.LBB0_630:
	v_rsq_f32_e32 v0, v110
	v_and_b32_e32 v111, 0xffff0000, v18
	s_lshl_b32 s10, s1, 2
	s_ashr_i32 s1, s9, 7
	v_mul_f32_e32 v110, 0x45800000, v0
	v_cndmask_b32_e32 v0, v0, v110, vcc
	v_mul_f32_e32 v0, v235, v0
	v_mul_f32_e32 v0, 0x3dd53b94, v0
	v_lshlrev_b32_e32 v110, 16, v18
	v_lshlrev_b32_e32 v18, 16, v19
	v_and_b32_e32 v19, 0xffff0000, v19
	v_pk_mul_f32 v[18:19], v[0:1], v[18:19] op_sel_hi:[0,1]
	v_pk_mul_f32 v[110:111], v[0:1], v[110:111] op_sel_hi:[0,1]
	v_pk_mul_f32 v[18:19], v[134:135], v[18:19]
	v_pk_mul_f32 v[110:111], v[132:133], v[110:111]
	v_cvt_pk_bf16_f32 v133, v18, v19
	v_lshlrev_b32_e32 v18, 16, v20
	v_and_b32_e32 v19, 0xffff0000, v20
	v_pk_mul_f32 v[18:19], v[0:1], v[18:19] op_sel_hi:[0,1]
	v_pk_mul_f32 v[18:19], v[196:197], v[18:19]
	v_lshlrev_b32_e32 v20, 16, v49
	v_cvt_pk_bf16_f32 v134, v18, v19
	v_lshlrev_b32_e32 v18, 16, v21
	v_and_b32_e32 v19, 0xffff0000, v21
	v_pk_mul_f32 v[18:19], v[0:1], v[18:19] op_sel_hi:[0,1]
	v_pk_mul_f32 v[18:19], v[198:199], v[18:19]
	v_and_b32_e32 v21, 0xffff0000, v49
	v_cvt_pk_bf16_f32 v135, v18, v19
	v_lshlrev_b32_e32 v18, 16, v6
	v_and_b32_e32 v19, 0xffff0000, v6
	v_lshlrev_b32_e32 v6, 16, v7
	v_and_b32_e32 v7, 0xffff0000, v7
	v_pk_mul_f32 v[6:7], v[0:1], v[6:7] op_sel_hi:[0,1]
	v_pk_mul_f32 v[18:19], v[0:1], v[18:19] op_sel_hi:[0,1]
	v_pk_mul_f32 v[6:7], v[138:139], v[6:7]
	v_pk_mul_f32 v[18:19], v[136:137], v[18:19]
	v_cvt_pk_bf16_f32 v137, v6, v7
	v_lshlrev_b32_e32 v6, 16, v8
	v_and_b32_e32 v7, 0xffff0000, v8
	v_pk_mul_f32 v[6:7], v[0:1], v[6:7] op_sel_hi:[0,1]
	v_pk_mul_f32 v[6:7], v[192:193], v[6:7]
	v_lshlrev_b32_e32 v8, 16, v46
	v_cvt_pk_bf16_f32 v138, v6, v7
	v_lshlrev_b32_e32 v6, 16, v9
	v_and_b32_e32 v7, 0xffff0000, v9
	v_pk_mul_f32 v[6:7], v[0:1], v[6:7] op_sel_hi:[0,1]
	v_pk_mul_f32 v[6:7], v[194:195], v[6:7]
	v_and_b32_e32 v9, 0xffff0000, v46
	v_cvt_pk_bf16_f32 v139, v6, v7
	v_lshlrev_b32_e32 v6, 16, v14
	v_and_b32_e32 v7, 0xffff0000, v14
	v_pk_mul_f32 v[6:7], v[0:1], v[6:7] op_sel_hi:[0,1]
	v_pk_mul_f32 v[6:7], v[140:141], v[6:7]
	v_pk_mul_f32 v[8:9], v[0:1], v[8:9] op_sel_hi:[0,1]
	v_cvt_pk_bf16_f32 v140, v6, v7
	v_lshlrev_b32_e32 v6, 16, v15
	v_and_b32_e32 v7, 0xffff0000, v15
	v_pk_mul_f32 v[6:7], v[0:1], v[6:7] op_sel_hi:[0,1]
	v_pk_mul_f32 v[6:7], v[142:143], v[6:7]
	v_pk_mul_f32 v[8:9], v[148:149], v[8:9]
	v_cvt_pk_bf16_f32 v141, v6, v7
	v_lshlrev_b32_e32 v6, 16, v16
	v_and_b32_e32 v7, 0xffff0000, v16
	v_pk_mul_f32 v[6:7], v[0:1], v[6:7] op_sel_hi:[0,1]
	v_pk_mul_f32 v[6:7], v[188:189], v[6:7]
	v_lshlrev_b32_e32 v16, 16, v48
	v_cvt_pk_bf16_f32 v142, v6, v7
	v_lshlrev_b32_e32 v6, 16, v17
	v_and_b32_e32 v7, 0xffff0000, v17
	v_pk_mul_f32 v[6:7], v[0:1], v[6:7] op_sel_hi:[0,1]
	v_pk_mul_f32 v[6:7], v[190:191], v[6:7]
	v_and_b32_e32 v17, 0xffff0000, v48
	v_cvt_pk_bf16_f32 v143, v6, v7
	v_lshlrev_b32_e32 v6, 16, v10
	v_and_b32_e32 v7, 0xffff0000, v10
	v_pk_mul_f32 v[6:7], v[0:1], v[6:7] op_sel_hi:[0,1]
	v_pk_mul_f32 v[6:7], v[144:145], v[6:7]
	v_pk_mul_f32 v[16:17], v[0:1], v[16:17] op_sel_hi:[0,1]
	v_cvt_pk_bf16_f32 v144, v6, v7
	v_lshlrev_b32_e32 v6, 16, v11
	v_and_b32_e32 v7, 0xffff0000, v11
	v_pk_mul_f32 v[6:7], v[0:1], v[6:7] op_sel_hi:[0,1]
	v_pk_mul_f32 v[6:7], v[146:147], v[6:7]
	v_pk_mul_f32 v[10:11], v[102:103], v[8:9]
	v_cvt_pk_bf16_f32 v145, v6, v7
	v_lshlrev_b32_e32 v6, 16, v12
	v_and_b32_e32 v7, 0xffff0000, v12
	v_pk_mul_f32 v[6:7], v[0:1], v[6:7] op_sel_hi:[0,1]
	v_pk_mul_f32 v[6:7], v[184:185], v[6:7]
	v_lshlrev_b32_e32 v12, 16, v47
	v_cvt_pk_bf16_f32 v146, v6, v7
	v_lshlrev_b32_e32 v6, 16, v13
	v_and_b32_e32 v7, 0xffff0000, v13
	v_pk_mul_f32 v[6:7], v[0:1], v[6:7] op_sel_hi:[0,1]
	v_pk_mul_f32 v[6:7], v[186:187], v[6:7]
	v_and_b32_e32 v13, 0xffff0000, v47
	v_cvt_pk_bf16_f32 v147, v6, v7
	v_lshlrev_b32_e32 v6, 16, v30
	v_and_b32_e32 v7, 0xffff0000, v30
	v_pk_mul_f32 v[6:7], v[0:1], v[6:7] op_sel_hi:[0,1]
	v_pk_mul_f32 v[6:7], v[152:153], v[6:7]
	v_pk_mul_f32 v[12:13], v[0:1], v[12:13] op_sel_hi:[0,1]
	v_cvt_pk_bf16_f32 v152, v6, v7
	v_lshlrev_b32_e32 v6, 16, v31
	v_and_b32_e32 v7, 0xffff0000, v31
	v_pk_mul_f32 v[6:7], v[0:1], v[6:7] op_sel_hi:[0,1]
	v_pk_mul_f32 v[6:7], v[154:155], v[6:7]
	v_pk_mul_f32 v[12:13], v[150:151], v[12:13]
	v_cvt_pk_bf16_f32 v153, v6, v7
	v_lshlrev_b32_e32 v6, 16, v32
	v_and_b32_e32 v7, 0xffff0000, v32
	v_pk_mul_f32 v[6:7], v[0:1], v[6:7] op_sel_hi:[0,1]
	v_pk_mul_f32 v[6:7], v[180:181], v[6:7]
	v_pk_mul_f32 v[14:15], v[104:105], v[12:13]
	v_cvt_pk_bf16_f32 v154, v6, v7
	v_lshlrev_b32_e32 v6, 16, v33
	v_and_b32_e32 v7, 0xffff0000, v33
	v_pk_mul_f32 v[6:7], v[0:1], v[6:7] op_sel_hi:[0,1]
	v_pk_mul_f32 v[6:7], v[182:183], v[6:7]
	v_pk_mul_f32 v[16:17], v[94:95], v[16:17]
	v_cvt_pk_bf16_f32 v155, v6, v7
	v_lshlrev_b32_e32 v6, 16, v22
	v_and_b32_e32 v7, 0xffff0000, v22
	v_pk_mul_f32 v[6:7], v[0:1], v[6:7] op_sel_hi:[0,1]
	v_pk_mul_f32 v[6:7], v[164:165], v[6:7]
	v_cvt_pk_bf16_f32 v136, v18, v19
	v_cvt_pk_bf16_f32 v164, v6, v7
	v_lshlrev_b32_e32 v6, 16, v23
	v_and_b32_e32 v7, 0xffff0000, v23
	v_pk_mul_f32 v[6:7], v[0:1], v[6:7] op_sel_hi:[0,1]
	v_pk_mul_f32 v[6:7], v[166:167], v[6:7]
	v_pk_mul_f32 v[18:19], v[86:87], v[16:17]
	v_cvt_pk_bf16_f32 v165, v6, v7
	v_lshlrev_b32_e32 v6, 16, v24
	v_and_b32_e32 v7, 0xffff0000, v24
	v_pk_mul_f32 v[6:7], v[0:1], v[6:7] op_sel_hi:[0,1]
	v_pk_mul_f32 v[6:7], v[176:177], v[6:7]
	v_pk_mul_f32 v[20:21], v[0:1], v[20:21] op_sel_hi:[0,1]
	v_cvt_pk_bf16_f32 v166, v6, v7
	v_lshlrev_b32_e32 v6, 16, v25
	v_and_b32_e32 v7, 0xffff0000, v25
	v_pk_mul_f32 v[6:7], v[0:1], v[6:7] op_sel_hi:[0,1]
	v_pk_mul_f32 v[6:7], v[178:179], v[6:7]
	v_pk_mul_f32 v[20:21], v[96:97], v[20:21]
	v_cvt_pk_bf16_f32 v167, v6, v7
	v_lshlrev_b32_e32 v6, 16, v42
	v_and_b32_e32 v7, 0xffff0000, v42
	v_pk_mul_f32 v[6:7], v[0:1], v[6:7] op_sel_hi:[0,1]
	v_pk_mul_f32 v[6:7], v[172:173], v[6:7]
	v_pk_mul_f32 v[22:23], v[88:89], v[20:21]
	v_cvt_pk_bf16_f32 v172, v6, v7
	v_lshlrev_b32_e32 v6, 16, v43
	v_and_b32_e32 v7, 0xffff0000, v43
	v_pk_mul_f32 v[6:7], v[0:1], v[6:7] op_sel_hi:[0,1]
	v_pk_mul_f32 v[6:7], v[174:175], v[6:7]
	s_xor_b64 s[2:3], s[2:3], -1
	v_cvt_pk_bf16_f32 v173, v6, v7
	v_lshlrev_b32_e32 v6, 16, v44
	v_and_b32_e32 v7, 0xffff0000, v44
	v_pk_mul_f32 v[6:7], v[0:1], v[6:7] op_sel_hi:[0,1]
	v_pk_mul_f32 v[6:7], v[168:169], v[6:7]
	v_lshlrev_b32_e32 v201, 3, v237
	v_cvt_pk_bf16_f32 v174, v6, v7
	v_lshlrev_b32_e32 v6, 16, v45
	v_and_b32_e32 v7, 0xffff0000, v45
	v_pk_mul_f32 v[6:7], v[0:1], v[6:7] op_sel_hi:[0,1]
	v_pk_mul_f32 v[6:7], v[170:171], v[6:7]
	v_cvt_pk_bf16_f32 v132, v110, v111
	v_cvt_pk_bf16_f32 v175, v6, v7
	v_lshlrev_b32_e32 v6, 16, v38
	v_and_b32_e32 v7, 0xffff0000, v38
	v_pk_mul_f32 v[6:7], v[0:1], v[6:7] op_sel_hi:[0,1]
	v_pk_mul_f32 v[6:7], v[160:161], v[6:7]
	s_add_i32 s1, s1, s10
	v_cvt_pk_bf16_f32 v160, v6, v7
	v_lshlrev_b32_e32 v6, 16, v39
	v_and_b32_e32 v7, 0xffff0000, v39
	v_pk_mul_f32 v[6:7], v[0:1], v[6:7] op_sel_hi:[0,1]
	v_pk_mul_f32 v[6:7], v[162:163], v[6:7]
	s_mov_b32 s6, 1
	v_cvt_pk_bf16_f32 v161, v6, v7
	v_lshlrev_b32_e32 v6, 16, v40
	v_and_b32_e32 v7, 0xffff0000, v40
	v_pk_mul_f32 v[6:7], v[0:1], v[6:7] op_sel_hi:[0,1]
	v_pk_mul_f32 v[6:7], v[156:157], v[6:7]
	v_mul_u32_u24_e32 v181, 0x90, v228
	v_cvt_pk_bf16_f32 v162, v6, v7
	v_lshlrev_b32_e32 v6, 16, v41
	v_and_b32_e32 v7, 0xffff0000, v41
	v_pk_mul_f32 v[6:7], v[0:1], v[6:7] op_sel_hi:[0,1]
	v_pk_mul_f32 v[6:7], v[158:159], v[6:7]
	s_or_b32 s7, s10, 2
	v_cvt_pk_bf16_f32 v163, v6, v7
	v_lshlrev_b32_e32 v6, 16, v26
	v_and_b32_e32 v7, 0xffff0000, v26
	v_pk_mul_f32 v[6:7], v[0:1], v[6:7] op_sel_hi:[0,1]
	v_pk_mul_f32 v[6:7], v[106:107], v[6:7]
	s_add_i32 s9, s10, 4
	v_pk_fma_f32 v[10:11], v[98:99], v[6:7], v[10:11] neg_lo:[0,0,1] neg_hi:[0,0,1]
	v_pk_mul_f32 v[6:7], v[102:103], v[6:7]
	v_cvt_pk_bf16_f32 v148, v10, v11
	v_pk_fma_f32 v[6:7], v[98:99], v[8:9], v[6:7]
	v_lshlrev_b32_e32 v8, 16, v27
	v_and_b32_e32 v9, 0xffff0000, v27
	v_pk_mul_f32 v[8:9], v[0:1], v[8:9] op_sel_hi:[0,1]
	v_pk_mul_f32 v[8:9], v[108:109], v[8:9]
	v_cvt_pk_bf16_f32 v156, v6, v7
	v_pk_fma_f32 v[14:15], v[100:101], v[8:9], v[14:15] neg_lo:[0,0,1] neg_hi:[0,0,1]
	v_pk_mul_f32 v[8:9], v[104:105], v[8:9]
	v_lshlrev_b32_e32 v6, 16, v2
	v_pk_fma_f32 v[8:9], v[100:101], v[12:13], v[8:9]
	v_and_b32_e32 v7, 0xffff0000, v2
	v_cvt_pk_bf16_f32 v157, v8, v9
	v_lshlrev_b32_e32 v8, 16, v34
	v_and_b32_e32 v9, 0xffff0000, v34
	v_pk_mul_f32 v[8:9], v[0:1], v[8:9] op_sel_hi:[0,1]
	v_pk_mul_f32 v[6:7], v[0:1], v[6:7] op_sel_hi:[0,1]
	v_pk_mul_f32 v[8:9], v[78:79], v[8:9]
	v_lshlrev_b32_e32 v12, 16, v28
	v_and_b32_e32 v13, 0xffff0000, v28
	v_pk_mul_f32 v[6:7], v[74:75], v[6:7]
	v_pk_mul_f32 v[10:11], v[70:71], v[8:9]
	v_pk_mul_f32 v[12:13], v[0:1], v[12:13] op_sel_hi:[0,1]
	v_pk_fma_f32 v[10:11], v[66:67], v[6:7], v[10:11] neg_lo:[0,0,1] neg_hi:[0,0,1]
	v_pk_mul_f32 v[6:7], v[70:71], v[6:7]
	v_pk_mul_f32 v[12:13], v[90:91], v[12:13]
	v_pk_fma_f32 v[6:7], v[66:67], v[8:9], v[6:7]
	v_lshlrev_b32_e32 v8, 16, v35
	v_and_b32_e32 v9, 0xffff0000, v35
	v_pk_fma_f32 v[18:19], v[82:83], v[12:13], v[18:19] neg_lo:[0,0,1] neg_hi:[0,0,1]
	v_pk_mul_f32 v[12:13], v[86:87], v[12:13]
	v_lshlrev_b32_e32 v2, 16, v3
	v_and_b32_e32 v3, 0xffff0000, v3
	v_pk_mul_f32 v[8:9], v[0:1], v[8:9] op_sel_hi:[0,1]
	v_pk_fma_f32 v[12:13], v[82:83], v[16:17], v[12:13]
	v_lshlrev_b32_e32 v16, 16, v29
	v_and_b32_e32 v17, 0xffff0000, v29
	v_pk_mul_f32 v[2:3], v[0:1], v[2:3] op_sel_hi:[0,1]
	v_pk_mul_f32 v[8:9], v[80:81], v[8:9]
	v_pk_mul_f32 v[16:17], v[0:1], v[16:17] op_sel_hi:[0,1]
	v_cvt_pk_bf16_f32 v158, v12, v13
	v_pk_mul_f32 v[2:3], v[76:77], v[2:3]
	v_pk_mul_f32 v[12:13], v[72:73], v[8:9]
	v_pk_mul_f32 v[16:17], v[92:93], v[16:17]
	v_cvt_pk_bf16_f32 v149, v14, v15
	v_pk_fma_f32 v[12:13], v[68:69], v[2:3], v[12:13] neg_lo:[0,0,1] neg_hi:[0,0,1]
	v_pk_mul_f32 v[2:3], v[72:73], v[2:3]
	v_lshlrev_b32_e32 v14, 16, v36
	v_and_b32_e32 v15, 0xffff0000, v36
	v_pk_fma_f32 v[22:23], v[84:85], v[16:17], v[22:23] neg_lo:[0,0,1] neg_hi:[0,0,1]
	v_pk_mul_f32 v[16:17], v[88:89], v[16:17]
	v_pk_fma_f32 v[2:3], v[68:69], v[8:9], v[2:3]
	v_lshlrev_b32_e32 v8, 16, v4
	v_and_b32_e32 v9, 0xffff0000, v4
	v_pk_mul_f32 v[14:15], v[0:1], v[14:15] op_sel_hi:[0,1]
	v_pk_fma_f32 v[16:17], v[84:85], v[20:21], v[16:17]
	v_pk_mul_f32 v[8:9], v[0:1], v[8:9] op_sel_hi:[0,1]
	v_pk_mul_f32 v[14:15], v[62:63], v[14:15]
	v_cvt_pk_bf16_f32 v159, v16, v17
	v_pk_mul_f32 v[8:9], v[58:59], v[8:9]
	v_pk_mul_f32 v[16:17], v[54:55], v[14:15]
	v_lshlrev_b32_e32 v4, 16, v5
	v_pk_fma_f32 v[16:17], v[50:51], v[8:9], v[16:17] neg_lo:[0,0,1] neg_hi:[0,0,1]
	v_pk_mul_f32 v[8:9], v[54:55], v[8:9]
	v_and_b32_e32 v5, 0xffff0000, v5
	v_pk_fma_f32 v[8:9], v[50:51], v[14:15], v[8:9]
	v_lshlrev_b32_e32 v14, 16, v37
	v_and_b32_e32 v15, 0xffff0000, v37
	v_pk_mul_f32 v[14:15], v[0:1], v[14:15] op_sel_hi:[0,1]
	v_pk_mul_f32 v[4:5], v[0:1], v[4:5] op_sel_hi:[0,1]
	v_pk_mul_f32 v[14:15], v[64:65], v[14:15]
	v_cvt_pk_bf16_f32 v150, v18, v19
	v_pk_mul_f32 v[4:5], v[60:61], v[4:5]
	v_pk_mul_f32 v[18:19], v[56:57], v[14:15]
	v_cvt_pk_bf16_f32 v177, v2, v3
	v_lshlrev_b32_e32 v2, 1, v228
	v_lshrrev_b32_e32 v3, 1, v231
	v_pk_fma_f32 v[18:19], v[52:53], v[4:5], v[18:19] neg_lo:[0,0,1] neg_hi:[0,0,1]
	v_pk_mul_f32 v[4:5], v[56:57], v[4:5]
	v_and_b32_e32 v0, 19, v231
	v_and_b32_e32 v2, 8, v2
	v_and_b32_e32 v3, 4, v3
	v_pk_fma_f32 v[4:5], v[52:53], v[14:15], v[4:5]
	v_or3_b32 v0, v0, v2, v3
	v_mov_b32_e32 v14, v1
	v_mov_b32_e32 v15, v1
	v_cvt_pk_bf16_f32 v151, v22, v23
	v_cvt_pk_bf16_f32 v168, v10, v11
	v_cvt_pk_bf16_f32 v169, v12, v13
	v_cvt_pk_bf16_f32 v170, v16, v17
	v_cvt_pk_bf16_f32 v171, v18, v19
	v_cvt_pk_bf16_f32 v176, v6, v7
	v_cvt_pk_bf16_f32 v178, v8, v9
	v_cvt_pk_bf16_f32 v179, v4, v5
	v_mul_u32_u24_e32 v180, 0x190, v0
	v_mov_b32_e32 v0, v1
	v_mov_b32_e32 v2, v1
	v_mov_b32_e32 v3, v1
	v_mov_b32_e32 v4, v1
	v_mov_b32_e32 v5, v1
	v_mov_b32_e32 v6, v1
	v_mov_b32_e32 v7, v1
	v_mov_b32_e32 v8, v1
	v_mov_b32_e32 v9, v1
	v_mov_b32_e32 v10, v1
	v_mov_b32_e32 v11, v1
	v_mov_b32_e32 v12, v1
	v_mov_b32_e32 v13, v1
	v_mov_b64_e32 v[30:31], v[14:15]
	v_mov_b64_e32 v[46:47], v[14:15]
	v_mov_b64_e32 v[62:63], v[14:15]
	v_mov_b64_e32 v[78:79], v[14:15]
	s_mov_b32 s11, 0
	v_mov_b32_e32 v182, 0
	v_mov_b64_e32 v[28:29], v[12:13]
	v_mov_b64_e32 v[26:27], v[10:11]
	v_mov_b64_e32 v[24:25], v[8:9]
	v_mov_b64_e32 v[22:23], v[6:7]
	v_mov_b64_e32 v[20:21], v[4:5]
	v_mov_b64_e32 v[18:19], v[2:3]
	v_mov_b64_e32 v[16:17], v[0:1]
	v_mov_b64_e32 v[44:45], v[12:13]
	v_mov_b64_e32 v[42:43], v[10:11]
	v_mov_b64_e32 v[40:41], v[8:9]
	v_mov_b64_e32 v[38:39], v[6:7]
	v_mov_b64_e32 v[36:37], v[4:5]
	v_mov_b64_e32 v[34:35], v[2:3]
	v_mov_b64_e32 v[32:33], v[0:1]
	v_mov_b64_e32 v[60:61], v[12:13]
	v_mov_b64_e32 v[58:59], v[10:11]
	v_mov_b64_e32 v[56:57], v[8:9]
	v_mov_b64_e32 v[54:55], v[6:7]
	v_mov_b64_e32 v[52:53], v[4:5]
	v_mov_b64_e32 v[50:51], v[2:3]
	v_mov_b64_e32 v[48:49], v[0:1]
	v_mov_b64_e32 v[76:77], v[12:13]
	v_mov_b64_e32 v[74:75], v[10:11]
	v_mov_b64_e32 v[72:73], v[8:9]
	v_mov_b64_e32 v[70:71], v[6:7]
	v_mov_b64_e32 v[68:69], v[4:5]
	v_mov_b64_e32 v[66:67], v[2:3]
	v_mov_b64_e32 v[64:65], v[0:1]
	s_mov_b32 s98, 0
	s_mov_b32 s99, 0xac00
.LBB0_631:
	s_add_i32 s10, s11, 1
	s_mov_b32 s16, s99
	v_add_u32_e32 v247, s16, v233
	v_add_u32_e32 v248, s16, v234
	v_add_u32_e32 v249, s16, v236
	v_add_u32_e32 v250, s16, v208
	v_add_u32_e32 v251, s16, v200
	s_cmp_lt_u32 s11, s7
	s_cselect_b64 s[16:17], -1, 0
	s_cmp_lg_u64 s[16:17], 0
	s_addc_u32 s6, s6, 0
	s_mov_b32 s22, s14
	s_mov_b32 s23, s15
	s_mov_b32 s26, s14
	s_mov_b32 s27, s15
	s_cmp_gt_i32 s11, s1
	s_cbranch_scc1 .Lattn1_stage_only
	s_mov_b32 s11, s98
	v_mov_b32_e32 v80, v213
	v_add3_u32 v0, s11, v180, v229
	ds_read_b128 v[2:5], v0
	ds_read_b128 v[6:9], v0 offset:32
	ds_read_b128 v[10:13], v0 offset:64
	ds_read_b128 v[184:187], v0 offset:96
	ds_read_b128 v[188:191], v0 offset:128
	ds_read_b128 v[192:195], v0 offset:160
	v_mov_b32_e32 v81, v80
	v_mov_b32_e32 v82, v80
	v_mov_b32_e32 v83, v80
	v_mov_b32_e32 v84, v80
	v_mov_b32_e32 v85, v80
	v_mov_b32_e32 v86, v80
	v_mov_b32_e32 v87, v80
	v_mov_b32_e32 v88, v80
	v_mov_b32_e32 v89, v80
	v_mov_b32_e32 v90, v80
	v_mov_b32_e32 v91, v80
	v_mov_b32_e32 v92, v80
	v_mov_b32_e32 v93, v80
	v_mov_b32_e32 v94, v80
	v_mov_b32_e32 v95, v80
	ds_read_b128 v[196:199], v0 offset:192
	s_waitcnt lgkmcnt(6)
	v_mfma_f32_32x32x16_bf16 v[96:111], v[2:5], v[132:135], v[80:95]
	s_mul_i32 s16, s6, 0x6000
	s_waitcnt vmcnt(4)
	ds_write_b128 v247, v[112:115]
	buffer_load_dwordx4 v[112:115], v230, s[20:23], s16 offen
	ds_read_b128 v[2:5], v0 offset:224
	s_waitcnt lgkmcnt(6)
	v_mfma_f32_32x32x16_bf16 v[96:111], v[6:9], v[136:139], v[96:111]
	ds_read_b128 v[6:9], v0 offset:256
	s_waitcnt lgkmcnt(6)
	v_mfma_f32_32x32x16_bf16 v[96:111], v[10:13], v[140:143], v[96:111]
	s_add_i32 s17, s16, 0x2000
	s_waitcnt vmcnt(4)
	ds_write_b128 v248, v[116:119]
	buffer_load_dwordx4 v[116:119], v230, s[20:23], s17 offen
	ds_read_b128 v[10:13], v0 offset:288
	s_waitcnt lgkmcnt(6)
	v_mfma_f32_32x32x16_bf16 v[96:111], v[184:187], v[144:147], v[96:111]
	ds_read_b128 v[184:187], v0 offset:320
	s_waitcnt lgkmcnt(6)
	v_mfma_f32_32x32x16_bf16 v[96:111], v[188:191], v[152:155], v[96:111]
	s_addk_i32 s16, 0x4000
	s_waitcnt vmcnt(4)
	ds_write_b128 v249, v[120:123]
	buffer_load_dwordx4 v[120:123], v230, s[20:23], s16 offen
	ds_read_b128 v[188:191], v0 offset:352
	s_waitcnt lgkmcnt(6)
	v_mfma_f32_32x32x16_bf16 v[96:111], v[192:195], v[164:167], v[96:111]
	ds_read_b128 v[192:195], v0 offset:12800
	s_waitcnt lgkmcnt(6)
	v_mfma_f32_32x32x16_bf16 v[96:111], v[196:199], v[172:175], v[96:111]
	s_lshl_b32 s16, s6, 7
	s_waitcnt vmcnt(4)
	ds_write_b128 v250, v[124:127] offset:25600
	buffer_load_dwordx4 v[124:127], v232, s[24:27], s16 offen
	ds_read_b128 v[196:199], v0 offset:12832
	s_waitcnt lgkmcnt(6)
	v_mfma_f32_32x32x16_bf16 v[96:111], v[2:5], v[160:163], v[96:111]
	ds_read_b128 v[2:5], v0 offset:12864
	s_waitcnt lgkmcnt(6)
	v_mfma_f32_32x32x16_bf16 v[96:111], v[6:9], v[148:151], v[96:111]
	s_add_i32 s16, s16, 0x100000
	s_waitcnt vmcnt(4)
	ds_write_b128 v251, v[128:131] offset:25600
	buffer_load_dwordx4 v[128:131], v232, s[24:27], s16 offen
	ds_read_b128 v[6:9], v0 offset:12896
	s_waitcnt lgkmcnt(6)
	v_mfma_f32_32x32x16_bf16 v[96:111], v[10:13], v[168:171], v[96:111]
	ds_read_b128 v[10:13], v0 offset:12928
	s_waitcnt lgkmcnt(6)
	v_mfma_f32_32x32x16_bf16 v[96:111], v[184:187], v[156:159], v[96:111]
	ds_read_b128 v[184:187], v0 offset:12960
	s_waitcnt lgkmcnt(6)
	v_mfma_f32_32x32x16_bf16 v[96:111], v[188:191], v[176:179], v[96:111]
	ds_read_b128 v[188:191], v0 offset:12992
	s_waitcnt lgkmcnt(6)
	v_mfma_f32_32x32x16_bf16 v[80:95], v[192:195], v[132:135], v[80:95]
	s_nop 8
	v_exp_f32_e32 v206, v96
	v_exp_f32_e32 v207, v97
	ds_read_b128 v[192:195], v0 offset:13024
	s_waitcnt lgkmcnt(6)
	v_mfma_f32_32x32x16_bf16 v[80:95], v[196:199], v[136:139], v[80:95]
	v_add_f32_e32 v14, v207, v206
	v_add_f32_e32 v96, v182, v14
	ds_read_b128 v[196:199], v0 offset:13056
	s_waitcnt lgkmcnt(6)
	v_mfma_f32_32x32x16_bf16 v[80:95], v[2:5], v[140:143], v[80:95]
	v_exp_f32_e32 v15, v98
	v_exp_f32_e32 v183, v99
	v_exp_f32_e32 v14, v100
	v_exp_f32_e32 v182, v101
	ds_read_b128 v[2:5], v0 offset:13088
	s_waitcnt lgkmcnt(6)
	v_mfma_f32_32x32x16_bf16 v[80:95], v[6:9], v[144:147], v[80:95]
	v_add_f32_e64 v6, v182, v14
	v_add_f32_e64 v7, v183, v15
	v_add_f32_e32 v7, v7, v96
	v_add_f32_e32 v98, v6, v7
	ds_read_b128 v[6:9], v0 offset:13120
	s_waitcnt lgkmcnt(6)
	v_mfma_f32_32x32x16_bf16 v[80:95], v[10:13], v[152:155], v[80:95]
	v_exp_f32_e32 v203, v102
	v_exp_f32_e32 v205, v103
	v_exp_f32_e32 v202, v104
	v_exp_f32_e32 v204, v105
	ds_read_b128 v[10:13], v0 offset:13152
	s_waitcnt lgkmcnt(6)
	v_mfma_f32_32x32x16_bf16 v[80:95], v[184:187], v[164:167], v[80:95]
	v_add_f32_e64 v96, v204, v202
	v_add_f32_e64 v97, v205, v203
	v_add_f32_e32 v0, v97, v98
	v_add_f32_e32 v0, v96, v0
	v_add3_u32 v209, s11, v181, v229
	ds_read_b128 v[96:99], v209 offset:25600
	s_waitcnt lgkmcnt(6)
	v_mfma_f32_32x32x16_bf16 v[80:95], v[188:191], v[172:175], v[80:95]
	v_exp_f32_e32 v187, v106
	v_exp_f32_e32 v189, v107
	v_exp_f32_e32 v186, v108
	v_exp_f32_e32 v188, v109
	ds_read_b128 v[100:103], v209 offset:30208
	s_waitcnt lgkmcnt(6)
	v_mfma_f32_32x32x16_bf16 v[80:95], v[192:195], v[160:163], v[80:95]
	v_add_f32_e64 v104, v188, v186
	v_add_f32_e64 v105, v189, v187
	v_add_f32_e32 v0, v105, v0
	v_add_f32_e32 v190, v104, v0
	ds_read_b128 v[104:107], v209 offset:34816
	s_waitcnt lgkmcnt(6)
	v_mfma_f32_32x32x16_bf16 v[80:95], v[196:199], v[148:151], v[80:95]
	s_barrier
	v_exp_f32_e32 v192, v110
	v_exp_f32_e32 v194, v111
	ds_read_b128 v[108:111], v209 offset:39424
	s_waitcnt lgkmcnt(6)
	v_mfma_f32_32x32x16_bf16 v[80:95], v[2:5], v[168:171], v[80:95]
	v_cvt_pk_bf16_f32 v2, v206, v207
	v_cvt_pk_bf16_f32 v3, v15, v183
	v_cvt_pk_bf16_f32 v4, v14, v182
	v_cvt_pk_bf16_f32 v5, v203, v205
	ds_read_b128 v[182:185], v209 offset:25632
	s_waitcnt lgkmcnt(6)
	v_mfma_f32_32x32x16_bf16 v[80:95], v[6:9], v[156:159], v[80:95]
	v_cvt_pk_bf16_f32 v6, v202, v204
	v_cvt_pk_bf16_f32 v7, v187, v189
	v_cvt_pk_bf16_f32 v8, v186, v188
	ds_read_b128 v[186:189], v209 offset:30240
	s_waitcnt lgkmcnt(6)
	v_mfma_f32_32x32x16_bf16 v[80:95], v[10:13], v[176:179], v[80:95]
	s_waitcnt lgkmcnt(5)
	v_mfma_f32_32x32x16_bf16 v[64:79], v[96:99], v[2:5], v[64:79]
	ds_read_b128 v[10:13], v209 offset:34848
	s_waitcnt lgkmcnt(5)
	v_mfma_f32_32x32x16_bf16 v[48:63], v[100:103], v[2:5], v[48:63]
	s_nop 6
	v_exp_f32_e32 v195, v80
	v_exp_f32_e32 v193, v81
	ds_read_b128 v[96:99], v209 offset:39456
	v_exp_f32_e32 v191, v82
	v_cvt_pk_bf16_f32 v9, v192, v194
	v_pk_add_f32 v[14:15], v[194:195], v[192:193]
	s_nop 0
	v_pk_add_f32 v[14:15], v[190:191], v[14:15]
	s_waitcnt lgkmcnt(5)
	v_mfma_f32_32x32x16_bf16 v[32:47], v[104:107], v[2:5], v[32:47]
	ds_read_b128 v[100:103], v209 offset:25664
	v_exp_f32_e32 v0, v83
	v_exp_f32_e32 v190, v84
	v_exp_f32_e32 v105, v85
	v_add_f32_e32 v107, v0, v190
	s_waitcnt lgkmcnt(5)
	v_mfma_f32_32x32x16_bf16 v[16:31], v[108:111], v[2:5], v[16:31]
	ds_read_b128 v[80:83], v209 offset:30272
	v_exp_f32_e32 v106, v86
	v_exp_f32_e32 v104, v87
	s_nop 0
	v_pk_add_f32 v[108:109], v[104:105], v[106:107]
	s_waitcnt lgkmcnt(5)
	v_mfma_f32_32x32x16_bf16 v[64:79], v[182:185], v[6:9], v[64:79]
	ds_read_b128 v[2:5], v209 offset:34880
	v_exp_f32_e32 v111, v88
	v_exp_f32_e32 v185, v89
	s_waitcnt lgkmcnt(5)
	v_mfma_f32_32x32x16_bf16 v[48:63], v[186:189], v[6:9], v[48:63]
	v_exp_f32_e32 v110, v90
	v_exp_f32_e32 v184, v91
	ds_read_b128 v[84:87], v209 offset:39488
	v_pk_add_f32 v[182:183], v[184:185], v[110:111]
	s_waitcnt lgkmcnt(5)
	v_mfma_f32_32x32x16_bf16 v[32:47], v[10:13], v[6:9], v[32:47]
	ds_read_b128 v[88:91], v209 offset:25696
	v_exp_f32_e32 v187, v92
	v_exp_f32_e32 v189, v93
	s_waitcnt lgkmcnt(5)
	v_mfma_f32_32x32x16_bf16 v[16:31], v[96:99], v[6:9], v[16:31]
	v_exp_f32_e32 v186, v94
	v_exp_f32_e32 v188, v95
	v_add_f32_e32 v92, v14, v15
	v_add_f32_e32 v92, v109, v92
	v_add_f32_e32 v6, v108, v92
	ds_read_b128 v[10:13], v209 offset:30304
	v_add_f32_e32 v6, v183, v6
	v_pk_add_f32 v[14:15], v[188:189], v[186:187]
	v_add_f32_e32 v6, v182, v6
	v_add_f32_e32 v6, v15, v6
	v_add_f32_e32 v182, v14, v6
	v_cvt_pk_bf16_f32 v6, v195, v193
	v_cvt_pk_bf16_f32 v7, v191, v0
	v_cvt_pk_bf16_f32 v8, v190, v105
	v_cvt_pk_bf16_f32 v9, v106, v104
	v_cvt_pk_bf16_f32 v92, v111, v185
	v_cvt_pk_bf16_f32 v93, v110, v184
	v_cvt_pk_bf16_f32 v94, v187, v189
	v_cvt_pk_bf16_f32 v95, v186, v188
	s_waitcnt lgkmcnt(5)
	v_mfma_f32_32x32x16_bf16 v[64:79], v[100:103], v[6:9], v[64:79]
	ds_read_b128 v[96:99], v209 offset:34912
	s_waitcnt lgkmcnt(5)
	v_mfma_f32_32x32x16_bf16 v[48:63], v[80:83], v[6:9], v[48:63]
	ds_read_b128 v[100:103], v209 offset:39520
	s_waitcnt lgkmcnt(5)
	v_mfma_f32_32x32x16_bf16 v[32:47], v[2:5], v[6:9], v[32:47]
	s_waitcnt lgkmcnt(4)
	v_mfma_f32_32x32x16_bf16 v[16:31], v[84:87], v[6:9], v[16:31]
	s_waitcnt lgkmcnt(3)
	v_mfma_f32_32x32x16_bf16 v[64:79], v[88:91], v[92:95], v[64:79]
	s_waitcnt lgkmcnt(2)
	v_mfma_f32_32x32x16_bf16 v[48:63], v[10:13], v[92:95], v[48:63]
	s_waitcnt lgkmcnt(1)
	v_mfma_f32_32x32x16_bf16 v[32:47], v[96:99], v[92:95], v[32:47]
	s_waitcnt lgkmcnt(0)
	v_mfma_f32_32x32x16_bf16 v[16:31], v[100:103], v[92:95], v[16:31]
.LBB0_633:
	s_mov_b32 s98, s99
	s_add_i32 s99, s99, 0xac00
	s_cmp_eq_u32 s99, 0x20400
	s_cselect_b32 s99, 0, s99
	s_cmp_eq_u32 s9, s10
	s_waitcnt lgkmcnt(0)
	s_cbranch_scc1 .Lattn1_exit
	s_mov_b32 s11, s10
	s_branch .LBB0_631
.Lattn1_stage_only:
	s_mul_i32 s16, s6, 0x6000
	s_waitcnt vmcnt(4)
	ds_write_b128 v247, v[112:115]
	buffer_load_dwordx4 v[112:115], v230, s[20:23], s16 offen
	s_add_i32 s17, s16, 0x2000
	s_waitcnt vmcnt(4)
	ds_write_b128 v248, v[116:119]
	buffer_load_dwordx4 v[116:119], v230, s[20:23], s17 offen
	s_addk_i32 s16, 0x4000
	s_waitcnt vmcnt(4)
	ds_write_b128 v249, v[120:123]
	buffer_load_dwordx4 v[120:123], v230, s[20:23], s16 offen
	s_lshl_b32 s16, s6, 7
	s_waitcnt vmcnt(4)
	ds_write_b128 v250, v[124:127] offset:25600
	buffer_load_dwordx4 v[124:127], v232, s[24:27], s16 offen
	s_add_i32 s16, s16, 0x100000
	s_waitcnt vmcnt(4)
	ds_write_b128 v251, v[128:131] offset:25600
	buffer_load_dwordx4 v[128:131], v232, s[24:27], s16 offen
	s_waitcnt lgkmcnt(0)
	s_barrier
	s_branch .LBB0_633
.Lattn1_exit:
	s_barrier

.LBB0_708:
	v_rsq_f32_e32 v0, v0
	v_and_b32_e32 v111, 0xffff0000, v42
	s_lshl_b32 s8, s1, 2
	s_ashr_i32 s1, s6, 7
	v_mul_f32_e32 v110, 0x45800000, v0
	v_cndmask_b32_e32 v0, v0, v110, vcc
	v_mul_f32_e32 v0, v230, v0
	v_mul_f32_e32 v0, 0x3dd53b94, v0
	v_lshlrev_b32_e32 v110, 16, v42
	v_lshlrev_b32_e32 v42, 16, v43
	v_and_b32_e32 v43, 0xffff0000, v43
	v_pk_mul_f32 v[42:43], v[0:1], v[42:43] op_sel_hi:[0,1]
	v_pk_mul_f32 v[110:111], v[0:1], v[110:111] op_sel_hi:[0,1]
	v_pk_mul_f32 v[42:43], v[134:135], v[42:43]
	v_pk_mul_f32 v[110:111], v[132:133], v[110:111]
	v_cvt_pk_bf16_f32 v133, v42, v43
	v_lshlrev_b32_e32 v42, 16, v44
	v_and_b32_e32 v43, 0xffff0000, v44
	v_pk_mul_f32 v[42:43], v[0:1], v[42:43] op_sel_hi:[0,1]
	v_pk_mul_f32 v[42:43], v[196:197], v[42:43]
	v_lshlrev_b32_e32 v201, 3, v231
	v_cvt_pk_bf16_f32 v134, v42, v43
	v_lshlrev_b32_e32 v42, 16, v45
	v_and_b32_e32 v43, 0xffff0000, v45
	v_pk_mul_f32 v[42:43], v[0:1], v[42:43] op_sel_hi:[0,1]
	v_pk_mul_f32 v[42:43], v[198:199], v[42:43]
	v_cvt_pk_bf16_f32 v132, v110, v111
	v_cvt_pk_bf16_f32 v135, v42, v43
	v_lshlrev_b32_e32 v42, 16, v18
	v_and_b32_e32 v43, 0xffff0000, v18
	v_lshlrev_b32_e32 v18, 16, v19
	v_and_b32_e32 v19, 0xffff0000, v19
	v_pk_mul_f32 v[18:19], v[0:1], v[18:19] op_sel_hi:[0,1]
	v_pk_mul_f32 v[42:43], v[0:1], v[42:43] op_sel_hi:[0,1]
	v_pk_mul_f32 v[18:19], v[138:139], v[18:19]
	v_pk_mul_f32 v[42:43], v[136:137], v[42:43]
	v_cvt_pk_bf16_f32 v137, v18, v19
	v_lshlrev_b32_e32 v18, 16, v20
	v_and_b32_e32 v19, 0xffff0000, v20
	v_pk_mul_f32 v[18:19], v[0:1], v[18:19] op_sel_hi:[0,1]
	v_pk_mul_f32 v[18:19], v[192:193], v[18:19]
	v_cvt_pk_bf16_f32 v136, v42, v43
	v_cvt_pk_bf16_f32 v138, v18, v19
	v_lshlrev_b32_e32 v18, 16, v21
	v_and_b32_e32 v19, 0xffff0000, v21
	v_pk_mul_f32 v[18:19], v[0:1], v[18:19] op_sel_hi:[0,1]
	v_pk_mul_f32 v[18:19], v[194:195], v[18:19]
	s_add_i32 s1, s1, s8
	v_cvt_pk_bf16_f32 v139, v18, v19
	v_lshlrev_b32_e32 v18, 16, v38
	v_and_b32_e32 v19, 0xffff0000, v38
	v_pk_mul_f32 v[18:19], v[0:1], v[18:19] op_sel_hi:[0,1]
	v_pk_mul_f32 v[18:19], v[140:141], v[18:19]
	s_mov_b32 s6, 1
	v_cvt_pk_bf16_f32 v140, v18, v19
	v_lshlrev_b32_e32 v18, 16, v39
	v_and_b32_e32 v19, 0xffff0000, v39
	v_pk_mul_f32 v[18:19], v[0:1], v[18:19] op_sel_hi:[0,1]
	v_pk_mul_f32 v[18:19], v[142:143], v[18:19]
	s_or_b32 s7, s8, 2
	v_cvt_pk_bf16_f32 v141, v18, v19
	v_lshlrev_b32_e32 v18, 16, v40
	v_and_b32_e32 v19, 0xffff0000, v40
	v_pk_mul_f32 v[18:19], v[0:1], v[18:19] op_sel_hi:[0,1]
	v_pk_mul_f32 v[18:19], v[188:189], v[18:19]
	s_add_i32 s8, s8, 4
	v_cvt_pk_bf16_f32 v142, v18, v19
	v_lshlrev_b32_e32 v18, 16, v41
	v_and_b32_e32 v19, 0xffff0000, v41
	v_pk_mul_f32 v[18:19], v[0:1], v[18:19] op_sel_hi:[0,1]
	v_pk_mul_f32 v[18:19], v[190:191], v[18:19]
	s_mov_b32 s10, 0
	v_cvt_pk_bf16_f32 v143, v18, v19
	v_lshlrev_b32_e32 v18, 16, v26
	v_and_b32_e32 v19, 0xffff0000, v26
	v_pk_mul_f32 v[18:19], v[0:1], v[18:19] op_sel_hi:[0,1]
	v_pk_mul_f32 v[18:19], v[144:145], v[18:19]
	s_nop 0
	v_cvt_pk_bf16_f32 v144, v18, v19
	v_lshlrev_b32_e32 v18, 16, v27
	v_and_b32_e32 v19, 0xffff0000, v27
	v_pk_mul_f32 v[18:19], v[0:1], v[18:19] op_sel_hi:[0,1]
	v_pk_mul_f32 v[18:19], v[146:147], v[18:19]
	s_nop 0
	v_cvt_pk_bf16_f32 v145, v18, v19
	v_lshlrev_b32_e32 v18, 16, v28
	v_and_b32_e32 v19, 0xffff0000, v28
	v_pk_mul_f32 v[18:19], v[0:1], v[18:19] op_sel_hi:[0,1]
	v_pk_mul_f32 v[18:19], v[184:185], v[18:19]
	s_nop 0
	v_cvt_pk_bf16_f32 v146, v18, v19
	v_lshlrev_b32_e32 v18, 16, v29
	v_and_b32_e32 v19, 0xffff0000, v29
	v_pk_mul_f32 v[18:19], v[0:1], v[18:19] op_sel_hi:[0,1]
	v_pk_mul_f32 v[18:19], v[186:187], v[18:19]
	s_nop 0
	v_cvt_pk_bf16_f32 v147, v18, v19
	v_lshlrev_b32_e32 v18, 16, v34
	v_and_b32_e32 v19, 0xffff0000, v34
	v_pk_mul_f32 v[18:19], v[0:1], v[18:19] op_sel_hi:[0,1]
	v_pk_mul_f32 v[18:19], v[148:149], v[18:19]
	s_nop 0
	v_cvt_pk_bf16_f32 v148, v18, v19
	v_lshlrev_b32_e32 v18, 16, v35
	v_and_b32_e32 v19, 0xffff0000, v35
	v_pk_mul_f32 v[18:19], v[0:1], v[18:19] op_sel_hi:[0,1]
	v_pk_mul_f32 v[18:19], v[150:151], v[18:19]
	s_nop 0
	v_cvt_pk_bf16_f32 v149, v18, v19
	v_lshlrev_b32_e32 v18, 16, v36
	v_and_b32_e32 v19, 0xffff0000, v36
	v_pk_mul_f32 v[18:19], v[0:1], v[18:19] op_sel_hi:[0,1]
	v_pk_mul_f32 v[18:19], v[180:181], v[18:19]
	v_mul_u32_u24_e32 v181, 0x90, v205
	v_cvt_pk_bf16_f32 v150, v18, v19
	v_lshlrev_b32_e32 v18, 16, v37
	v_and_b32_e32 v19, 0xffff0000, v37
	v_pk_mul_f32 v[18:19], v[0:1], v[18:19] op_sel_hi:[0,1]
	v_pk_mul_f32 v[18:19], v[182:183], v[18:19]
	v_mov_b32_e32 v182, 0
	v_cvt_pk_bf16_f32 v151, v18, v19
	v_lshlrev_b32_e32 v18, 16, v22
	v_and_b32_e32 v19, 0xffff0000, v22
	v_pk_mul_f32 v[18:19], v[0:1], v[18:19] op_sel_hi:[0,1]
	v_pk_mul_f32 v[18:19], v[152:153], v[18:19]
	v_lshlrev_b32_e32 v22, 16, v48
	v_cvt_pk_bf16_f32 v152, v18, v19
	v_lshlrev_b32_e32 v18, 16, v23
	v_and_b32_e32 v19, 0xffff0000, v23
	v_pk_mul_f32 v[18:19], v[0:1], v[18:19] op_sel_hi:[0,1]
	v_pk_mul_f32 v[18:19], v[154:155], v[18:19]
	v_and_b32_e32 v23, 0xffff0000, v48
	v_cvt_pk_bf16_f32 v153, v18, v19
	v_lshlrev_b32_e32 v18, 16, v24
	v_and_b32_e32 v19, 0xffff0000, v24
	v_pk_mul_f32 v[18:19], v[0:1], v[18:19] op_sel_hi:[0,1]
	v_pk_mul_f32 v[18:19], v[176:177], v[18:19]
	v_pk_mul_f32 v[22:23], v[0:1], v[22:23] op_sel_hi:[0,1]
	v_cvt_pk_bf16_f32 v154, v18, v19
	v_lshlrev_b32_e32 v18, 16, v25
	v_and_b32_e32 v19, 0xffff0000, v25
	v_pk_mul_f32 v[18:19], v[0:1], v[18:19] op_sel_hi:[0,1]
	v_pk_mul_f32 v[18:19], v[178:179], v[18:19]
	v_pk_mul_f32 v[22:23], v[94:95], v[22:23]
	v_cvt_pk_bf16_f32 v155, v18, v19
	v_lshlrev_b32_e32 v18, 16, v30
	v_and_b32_e32 v19, 0xffff0000, v30
	v_pk_mul_f32 v[18:19], v[0:1], v[18:19] op_sel_hi:[0,1]
	v_pk_mul_f32 v[18:19], v[156:157], v[18:19]
	v_pk_mul_f32 v[24:25], v[86:87], v[22:23]
	v_cvt_pk_bf16_f32 v156, v18, v19
	v_lshlrev_b32_e32 v18, 16, v31
	v_and_b32_e32 v19, 0xffff0000, v31
	v_pk_mul_f32 v[18:19], v[0:1], v[18:19] op_sel_hi:[0,1]
	v_pk_mul_f32 v[18:19], v[158:159], v[18:19]
	s_nop 0
	v_cvt_pk_bf16_f32 v157, v18, v19
	v_lshlrev_b32_e32 v18, 16, v32
	v_and_b32_e32 v19, 0xffff0000, v32
	v_pk_mul_f32 v[18:19], v[0:1], v[18:19] op_sel_hi:[0,1]
	v_pk_mul_f32 v[18:19], v[172:173], v[18:19]
	s_nop 0
	v_cvt_pk_bf16_f32 v158, v18, v19
	v_lshlrev_b32_e32 v18, 16, v33
	v_and_b32_e32 v19, 0xffff0000, v33
	v_pk_mul_f32 v[18:19], v[0:1], v[18:19] op_sel_hi:[0,1]
	v_pk_mul_f32 v[18:19], v[174:175], v[18:19]
	s_nop 0
	v_cvt_pk_bf16_f32 v159, v18, v19
	v_lshlrev_b32_e32 v18, 16, v14
	v_and_b32_e32 v19, 0xffff0000, v14
	v_lshlrev_b32_e32 v14, 16, v15
	v_and_b32_e32 v15, 0xffff0000, v15
	v_pk_mul_f32 v[14:15], v[0:1], v[14:15] op_sel_hi:[0,1]
	v_pk_mul_f32 v[18:19], v[0:1], v[18:19] op_sel_hi:[0,1]
	v_pk_mul_f32 v[14:15], v[162:163], v[14:15]
	v_pk_mul_f32 v[18:19], v[160:161], v[18:19]
	v_cvt_pk_bf16_f32 v161, v14, v15
	v_lshlrev_b32_e32 v14, 16, v16
	v_and_b32_e32 v15, 0xffff0000, v16
	v_pk_mul_f32 v[14:15], v[0:1], v[14:15] op_sel_hi:[0,1]
	v_pk_mul_f32 v[14:15], v[168:169], v[14:15]
	v_lshlrev_b32_e32 v16, 16, v46
	v_cvt_pk_bf16_f32 v162, v14, v15
	v_lshlrev_b32_e32 v14, 16, v17
	v_and_b32_e32 v15, 0xffff0000, v17
	v_pk_mul_f32 v[14:15], v[0:1], v[14:15] op_sel_hi:[0,1]
	v_pk_mul_f32 v[14:15], v[170:171], v[14:15]
	v_and_b32_e32 v17, 0xffff0000, v46
	v_cvt_pk_bf16_f32 v163, v14, v15
	v_lshlrev_b32_e32 v14, 16, v6
	v_and_b32_e32 v15, 0xffff0000, v6
	v_pk_mul_f32 v[16:17], v[0:1], v[16:17] op_sel_hi:[0,1]
	v_pk_mul_f32 v[14:15], v[0:1], v[14:15] op_sel_hi:[0,1]
	v_pk_mul_f32 v[16:17], v[164:165], v[16:17]
	v_cvt_pk_bf16_f32 v160, v18, v19
	v_pk_mul_f32 v[14:15], v[106:107], v[14:15]
	v_pk_mul_f32 v[18:19], v[102:103], v[16:17]
	v_lshlrev_b32_e32 v6, 16, v7
	v_pk_fma_f32 v[18:19], v[98:99], v[14:15], v[18:19] neg_lo:[0,0,1] neg_hi:[0,0,1]
	v_pk_mul_f32 v[14:15], v[102:103], v[14:15]
	v_and_b32_e32 v7, 0xffff0000, v7
	v_pk_fma_f32 v[14:15], v[98:99], v[16:17], v[14:15]
	v_lshlrev_b32_e32 v16, 16, v47
	v_and_b32_e32 v17, 0xffff0000, v47
	v_pk_mul_f32 v[16:17], v[0:1], v[16:17] op_sel_hi:[0,1]
	v_pk_mul_f32 v[6:7], v[0:1], v[6:7] op_sel_hi:[0,1]
	v_pk_mul_f32 v[16:17], v[166:167], v[16:17]
	v_pk_mul_f32 v[6:7], v[108:109], v[6:7]
	v_pk_mul_f32 v[20:21], v[104:105], v[16:17]
	v_cvt_pk_bf16_f32 v168, v14, v15
	v_pk_fma_f32 v[20:21], v[100:101], v[6:7], v[20:21] neg_lo:[0,0,1] neg_hi:[0,0,1]
	v_pk_mul_f32 v[6:7], v[104:105], v[6:7]
	v_cvt_pk_bf16_f32 v164, v18, v19
	v_pk_fma_f32 v[6:7], v[100:101], v[16:17], v[6:7]
	v_lshlrev_b32_e32 v16, 16, v8
	v_and_b32_e32 v17, 0xffff0000, v8
	v_pk_mul_f32 v[16:17], v[0:1], v[16:17] op_sel_hi:[0,1]
	v_pk_mul_f32 v[16:17], v[90:91], v[16:17]
	v_lshlrev_b32_e32 v8, 16, v9
	v_pk_fma_f32 v[24:25], v[82:83], v[16:17], v[24:25] neg_lo:[0,0,1] neg_hi:[0,0,1]
	v_pk_mul_f32 v[16:17], v[86:87], v[16:17]
	v_and_b32_e32 v9, 0xffff0000, v9
	v_pk_fma_f32 v[16:17], v[82:83], v[22:23], v[16:17]
	v_lshlrev_b32_e32 v22, 16, v49
	v_and_b32_e32 v23, 0xffff0000, v49
	v_pk_mul_f32 v[22:23], v[0:1], v[22:23] op_sel_hi:[0,1]
	v_pk_mul_f32 v[8:9], v[0:1], v[8:9] op_sel_hi:[0,1]
	v_pk_mul_f32 v[22:23], v[96:97], v[22:23]
	v_pk_mul_f32 v[8:9], v[92:93], v[8:9]
	v_pk_mul_f32 v[26:27], v[88:89], v[22:23]
	v_cvt_pk_bf16_f32 v169, v6, v7
	v_pk_fma_f32 v[26:27], v[84:85], v[8:9], v[26:27] neg_lo:[0,0,1] neg_hi:[0,0,1]
	v_pk_mul_f32 v[8:9], v[88:89], v[8:9]
	v_lshlrev_b32_e32 v6, 16, v2
	v_pk_fma_f32 v[8:9], v[84:85], v[22:23], v[8:9]
	v_and_b32_e32 v7, 0xffff0000, v2
	v_cvt_pk_bf16_f32 v171, v8, v9
	v_lshlrev_b32_e32 v8, 16, v10
	v_and_b32_e32 v9, 0xffff0000, v10
	v_pk_mul_f32 v[8:9], v[0:1], v[8:9] op_sel_hi:[0,1]
	v_pk_mul_f32 v[6:7], v[0:1], v[6:7] op_sel_hi:[0,1]
	v_pk_mul_f32 v[8:9], v[78:79], v[8:9]
	v_pk_mul_f32 v[6:7], v[74:75], v[6:7]
	v_pk_mul_f32 v[14:15], v[70:71], v[8:9]
	v_lshlrev_b32_e32 v2, 16, v3
	v_pk_fma_f32 v[14:15], v[66:67], v[6:7], v[14:15] neg_lo:[0,0,1] neg_hi:[0,0,1]
	v_pk_mul_f32 v[6:7], v[70:71], v[6:7]
	v_and_b32_e32 v3, 0xffff0000, v3
	v_pk_fma_f32 v[6:7], v[66:67], v[8:9], v[6:7]
	v_lshlrev_b32_e32 v8, 16, v11
	v_and_b32_e32 v9, 0xffff0000, v11
	v_pk_mul_f32 v[8:9], v[0:1], v[8:9] op_sel_hi:[0,1]
	v_pk_mul_f32 v[2:3], v[0:1], v[2:3] op_sel_hi:[0,1]
	v_pk_mul_f32 v[8:9], v[80:81], v[8:9]
	v_pk_mul_f32 v[2:3], v[76:77], v[2:3]
	v_pk_mul_f32 v[10:11], v[72:73], v[8:9]
	v_cvt_pk_bf16_f32 v170, v16, v17
	v_pk_fma_f32 v[10:11], v[68:69], v[2:3], v[10:11] neg_lo:[0,0,1] neg_hi:[0,0,1]
	v_pk_mul_f32 v[2:3], v[72:73], v[2:3]
	v_lshlrev_b32_e32 v16, 16, v12
	v_and_b32_e32 v17, 0xffff0000, v12
	v_pk_fma_f32 v[2:3], v[68:69], v[8:9], v[2:3]
	v_lshlrev_b32_e32 v8, 16, v4
	v_and_b32_e32 v9, 0xffff0000, v4
	v_pk_mul_f32 v[16:17], v[0:1], v[16:17] op_sel_hi:[0,1]
	v_pk_mul_f32 v[8:9], v[0:1], v[8:9] op_sel_hi:[0,1]
	v_pk_mul_f32 v[16:17], v[62:63], v[16:17]
	v_lshlrev_b32_e32 v12, 16, v13
	v_and_b32_e32 v13, 0xffff0000, v13
	v_pk_mul_f32 v[8:9], v[58:59], v[8:9]
	v_pk_mul_f32 v[18:19], v[54:55], v[16:17]
	v_lshlrev_b32_e32 v4, 16, v5
	v_and_b32_e32 v5, 0xffff0000, v5
	v_pk_mul_f32 v[12:13], v[0:1], v[12:13] op_sel_hi:[0,1]
	v_pk_fma_f32 v[18:19], v[50:51], v[8:9], v[18:19] neg_lo:[0,0,1] neg_hi:[0,0,1]
	v_pk_mul_f32 v[8:9], v[54:55], v[8:9]
	v_pk_mul_f32 v[4:5], v[0:1], v[4:5] op_sel_hi:[0,1]
	v_pk_mul_f32 v[12:13], v[64:65], v[12:13]
	v_pk_fma_f32 v[8:9], v[50:51], v[16:17], v[8:9]
	v_pk_mul_f32 v[4:5], v[60:61], v[4:5]
	v_pk_mul_f32 v[16:17], v[56:57], v[12:13]
	v_cvt_pk_bf16_f32 v177, v2, v3
	v_lshlrev_b32_e32 v2, 1, v205
	v_lshrrev_b32_e32 v3, 1, v208
	v_pk_fma_f32 v[16:17], v[52:53], v[4:5], v[16:17] neg_lo:[0,0,1] neg_hi:[0,0,1]
	v_pk_mul_f32 v[4:5], v[56:57], v[4:5]
	v_and_b32_e32 v0, 19, v208
	v_and_b32_e32 v2, 8, v2
	v_and_b32_e32 v3, 4, v3
	v_pk_fma_f32 v[4:5], v[52:53], v[12:13], v[4:5]
	v_cvt_pk_bf16_f32 v172, v14, v15
	v_or3_b32 v0, v0, v2, v3
	v_mov_b32_e32 v14, v1
	v_mov_b32_e32 v15, v1
	v_cvt_pk_bf16_f32 v165, v20, v21
	v_cvt_pk_bf16_f32 v166, v24, v25
	v_cvt_pk_bf16_f32 v167, v26, v27
	v_cvt_pk_bf16_f32 v173, v10, v11
	v_cvt_pk_bf16_f32 v174, v18, v19
	v_cvt_pk_bf16_f32 v175, v16, v17
	v_cvt_pk_bf16_f32 v176, v6, v7
	v_cvt_pk_bf16_f32 v178, v8, v9
	v_cvt_pk_bf16_f32 v179, v4, v5
	v_mul_u32_u24_e32 v180, 0x190, v0
	v_mov_b32_e32 v0, v1
	v_mov_b32_e32 v2, v1
	v_mov_b32_e32 v3, v1
	v_mov_b32_e32 v4, v1
	v_mov_b32_e32 v5, v1
	v_mov_b32_e32 v6, v1
	v_mov_b32_e32 v7, v1
	v_mov_b32_e32 v8, v1
	v_mov_b32_e32 v9, v1
	v_mov_b32_e32 v10, v1
	v_mov_b32_e32 v11, v1
	v_mov_b32_e32 v12, v1
	v_mov_b32_e32 v13, v1
	v_mov_b64_e32 v[30:31], v[14:15]
	v_mov_b64_e32 v[46:47], v[14:15]
	v_mov_b64_e32 v[62:63], v[14:15]
	v_mov_b64_e32 v[78:79], v[14:15]
	v_mov_b64_e32 v[28:29], v[12:13]
	v_mov_b64_e32 v[26:27], v[10:11]
	v_mov_b64_e32 v[24:25], v[8:9]
	v_mov_b64_e32 v[22:23], v[6:7]
	v_mov_b64_e32 v[20:21], v[4:5]
	v_mov_b64_e32 v[18:19], v[2:3]
	v_mov_b64_e32 v[16:17], v[0:1]
	v_mov_b64_e32 v[44:45], v[12:13]
	v_mov_b64_e32 v[42:43], v[10:11]
	v_mov_b64_e32 v[40:41], v[8:9]
	v_mov_b64_e32 v[38:39], v[6:7]
	v_mov_b64_e32 v[36:37], v[4:5]
	v_mov_b64_e32 v[34:35], v[2:3]
	v_mov_b64_e32 v[32:33], v[0:1]
	v_mov_b64_e32 v[60:61], v[12:13]
	v_mov_b64_e32 v[58:59], v[10:11]
	v_mov_b64_e32 v[56:57], v[8:9]
	v_mov_b64_e32 v[54:55], v[6:7]
	v_mov_b64_e32 v[52:53], v[4:5]
	v_mov_b64_e32 v[50:51], v[2:3]
	v_mov_b64_e32 v[48:49], v[0:1]
	v_mov_b64_e32 v[76:77], v[12:13]
	v_mov_b64_e32 v[74:75], v[10:11]
	v_mov_b64_e32 v[72:73], v[8:9]
	v_mov_b64_e32 v[70:71], v[6:7]
	v_mov_b64_e32 v[68:69], v[4:5]
	v_mov_b64_e32 v[66:67], v[2:3]
	v_mov_b64_e32 v[64:65], v[0:1]
	s_mov_b32 s98, 0
	s_mov_b32 s99, 0xac00
.LBB0_709:
	s_add_i32 s9, s10, 1
	s_mov_b32 s11, s99
	v_add_u32_e32 v247, s11, v227
	v_add_u32_e32 v248, s11, v228
	v_add_u32_e32 v249, s11, v229
	v_add_u32_e32 v250, s11, v200
	v_add_u32_e32 v251, s11, v202
	s_cmp_lt_u32 s10, s7
	s_cselect_b64 s[16:17], -1, 0
	s_cmp_lg_u64 s[16:17], 0
	s_addc_u32 s6, s6, 0
	s_mov_b32 s22, s14
	s_mov_b32 s23, s15
	s_mov_b32 s26, s14
	s_mov_b32 s27, s15
	s_cmp_gt_i32 s10, s1
	s_cbranch_scc1 .Lattn2_stage_only
	s_mov_b32 s10, s98
	v_mov_b32_e32 v80, v213
	v_add3_u32 v0, s10, v180, v206
	ds_read_b128 v[2:5], v0
	ds_read_b128 v[6:9], v0 offset:32
	ds_read_b128 v[10:13], v0 offset:64
	ds_read_b128 v[184:187], v0 offset:96
	ds_read_b128 v[188:191], v0 offset:128
	ds_read_b128 v[192:195], v0 offset:160
	v_mov_b32_e32 v81, v80
	v_mov_b32_e32 v82, v80
	v_mov_b32_e32 v83, v80
	v_mov_b32_e32 v84, v80
	v_mov_b32_e32 v85, v80
	v_mov_b32_e32 v86, v80
	v_mov_b32_e32 v87, v80
	v_mov_b32_e32 v88, v80
	v_mov_b32_e32 v89, v80
	v_mov_b32_e32 v90, v80
	v_mov_b32_e32 v91, v80
	v_mov_b32_e32 v92, v80
	v_mov_b32_e32 v93, v80
	v_mov_b32_e32 v94, v80
	v_mov_b32_e32 v95, v80
	ds_read_b128 v[196:199], v0 offset:192
	s_waitcnt lgkmcnt(6)
	v_mfma_f32_32x32x16_bf16 v[96:111], v[2:5], v[132:135], v[80:95]
	s_mul_i32 s11, s6, 0x6000
	s_waitcnt vmcnt(4)
	ds_write_b128 v247, v[112:115]
	buffer_load_dwordx4 v[112:115], v207, s[20:23], s11 offen
	ds_read_b128 v[2:5], v0 offset:224
	s_waitcnt lgkmcnt(6)
	v_mfma_f32_32x32x16_bf16 v[96:111], v[6:9], v[136:139], v[96:111]
	ds_read_b128 v[6:9], v0 offset:256
	s_waitcnt lgkmcnt(6)
	v_mfma_f32_32x32x16_bf16 v[96:111], v[10:13], v[140:143], v[96:111]
	s_add_i32 s16, s11, 0x2000
	s_waitcnt vmcnt(4)
	ds_write_b128 v248, v[116:119]
	buffer_load_dwordx4 v[116:119], v207, s[20:23], s16 offen
	ds_read_b128 v[10:13], v0 offset:288
	s_waitcnt lgkmcnt(6)
	v_mfma_f32_32x32x16_bf16 v[96:111], v[184:187], v[144:147], v[96:111]
	ds_read_b128 v[184:187], v0 offset:320
	s_waitcnt lgkmcnt(6)
	v_mfma_f32_32x32x16_bf16 v[96:111], v[188:191], v[148:151], v[96:111]
	s_addk_i32 s11, 0x4000
	s_waitcnt vmcnt(4)
	ds_write_b128 v249, v[120:123]
	buffer_load_dwordx4 v[120:123], v207, s[20:23], s11 offen
	ds_read_b128 v[188:191], v0 offset:352
	s_waitcnt lgkmcnt(6)
	v_mfma_f32_32x32x16_bf16 v[96:111], v[192:195], v[152:155], v[96:111]
	ds_read_b128 v[192:195], v0 offset:12800
	s_waitcnt lgkmcnt(6)
	v_mfma_f32_32x32x16_bf16 v[96:111], v[196:199], v[156:159], v[96:111]
	s_lshl_b32 s11, s6, 7
	s_waitcnt vmcnt(4)
	ds_write_b128 v250, v[124:127] offset:25600
	buffer_load_dwordx4 v[124:127], v209, s[24:27], s11 offen
	ds_read_b128 v[196:199], v0 offset:12832
	s_waitcnt lgkmcnt(6)
	v_mfma_f32_32x32x16_bf16 v[96:111], v[2:5], v[160:163], v[96:111]
	ds_read_b128 v[2:5], v0 offset:12864
	s_waitcnt lgkmcnt(6)
	v_mfma_f32_32x32x16_bf16 v[96:111], v[6:9], v[164:167], v[96:111]
	s_add_i32 s11, s11, 0x100000
	s_waitcnt vmcnt(4)
	ds_write_b128 v251, v[128:131] offset:25600
	buffer_load_dwordx4 v[128:131], v209, s[24:27], s11 offen
	ds_read_b128 v[6:9], v0 offset:12896
	s_waitcnt lgkmcnt(6)
	v_mfma_f32_32x32x16_bf16 v[96:111], v[10:13], v[172:175], v[96:111]
	ds_read_b128 v[10:13], v0 offset:12928
	s_waitcnt lgkmcnt(6)
	v_mfma_f32_32x32x16_bf16 v[96:111], v[184:187], v[168:171], v[96:111]
	ds_read_b128 v[184:187], v0 offset:12960
	s_waitcnt lgkmcnt(6)
	v_mfma_f32_32x32x16_bf16 v[96:111], v[188:191], v[176:179], v[96:111]
	ds_read_b128 v[188:191], v0 offset:12992
	s_waitcnt lgkmcnt(6)
	v_mfma_f32_32x32x16_bf16 v[80:95], v[192:195], v[132:135], v[80:95]
	s_nop 8
	v_exp_f32_e32 v203, v96
	v_exp_f32_e32 v208, v97
	ds_read_b128 v[192:195], v0 offset:13024
	s_waitcnt lgkmcnt(6)
	v_mfma_f32_32x32x16_bf16 v[80:95], v[196:199], v[136:139], v[80:95]
	v_add_f32_e32 v14, v208, v203
	v_add_f32_e32 v96, v182, v14
	ds_read_b128 v[196:199], v0 offset:13056
	s_waitcnt lgkmcnt(6)
	v_mfma_f32_32x32x16_bf16 v[80:95], v[2:5], v[140:143], v[80:95]
	v_exp_f32_e32 v15, v98
	v_exp_f32_e32 v183, v99
	v_exp_f32_e32 v14, v100
	v_exp_f32_e32 v182, v101
	ds_read_b128 v[2:5], v0 offset:13088
	s_waitcnt lgkmcnt(6)
	v_mfma_f32_32x32x16_bf16 v[80:95], v[6:9], v[144:147], v[80:95]
	v_add_f32_e64 v6, v182, v14
	v_add_f32_e64 v7, v183, v15
	v_add_f32_e32 v7, v7, v96
	v_add_f32_e32 v98, v6, v7
	ds_read_b128 v[6:9], v0 offset:13120
	s_waitcnt lgkmcnt(6)
	v_mfma_f32_32x32x16_bf16 v[80:95], v[10:13], v[148:151], v[80:95]
	v_exp_f32_e32 v231, v102
	v_exp_f32_e32 v233, v103
	v_exp_f32_e32 v230, v104
	v_exp_f32_e32 v232, v105
	ds_read_b128 v[10:13], v0 offset:13152
	s_waitcnt lgkmcnt(6)
	v_mfma_f32_32x32x16_bf16 v[80:95], v[184:187], v[152:155], v[80:95]
	v_add_f32_e64 v96, v232, v230
	v_add_f32_e64 v97, v233, v231
	v_add_f32_e32 v0, v97, v98
	v_add_f32_e32 v0, v96, v0
	v_add3_u32 v234, s10, v181, v206
	ds_read_b128 v[96:99], v234 offset:25600
	s_waitcnt lgkmcnt(6)
	v_mfma_f32_32x32x16_bf16 v[80:95], v[188:191], v[156:159], v[80:95]
	v_exp_f32_e32 v187, v106
	v_exp_f32_e32 v189, v107
	v_exp_f32_e32 v186, v108
	v_exp_f32_e32 v188, v109
	ds_read_b128 v[100:103], v234 offset:30208
	s_waitcnt lgkmcnt(6)
	v_mfma_f32_32x32x16_bf16 v[80:95], v[192:195], v[160:163], v[80:95]
	v_add_f32_e64 v104, v188, v186
	v_add_f32_e64 v105, v189, v187
	v_add_f32_e32 v0, v105, v0
	v_add_f32_e32 v190, v104, v0
	ds_read_b128 v[104:107], v234 offset:34816
	s_waitcnt lgkmcnt(6)
	v_mfma_f32_32x32x16_bf16 v[80:95], v[196:199], v[164:167], v[80:95]
	s_barrier
	v_exp_f32_e32 v192, v110
	v_exp_f32_e32 v194, v111
	ds_read_b128 v[108:111], v234 offset:39424
	s_waitcnt lgkmcnt(6)
	v_mfma_f32_32x32x16_bf16 v[80:95], v[2:5], v[172:175], v[80:95]
	v_cvt_pk_bf16_f32 v2, v203, v208
	v_cvt_pk_bf16_f32 v3, v15, v183
	v_cvt_pk_bf16_f32 v4, v14, v182
	v_cvt_pk_bf16_f32 v5, v231, v233
	ds_read_b128 v[182:185], v234 offset:25632
	s_waitcnt lgkmcnt(6)
	v_mfma_f32_32x32x16_bf16 v[80:95], v[6:9], v[168:171], v[80:95]
	v_cvt_pk_bf16_f32 v6, v230, v232
	v_cvt_pk_bf16_f32 v7, v187, v189
	v_cvt_pk_bf16_f32 v8, v186, v188
	ds_read_b128 v[186:189], v234 offset:30240
	s_waitcnt lgkmcnt(6)
	v_mfma_f32_32x32x16_bf16 v[80:95], v[10:13], v[176:179], v[80:95]
	s_waitcnt lgkmcnt(5)
	v_mfma_f32_32x32x16_bf16 v[64:79], v[96:99], v[2:5], v[64:79]
	ds_read_b128 v[10:13], v234 offset:34848
	s_waitcnt lgkmcnt(5)
	v_mfma_f32_32x32x16_bf16 v[48:63], v[100:103], v[2:5], v[48:63]
	s_nop 6
	v_exp_f32_e32 v195, v80
	v_exp_f32_e32 v193, v81
	ds_read_b128 v[96:99], v234 offset:39456
	v_exp_f32_e32 v191, v82
	v_cvt_pk_bf16_f32 v9, v192, v194
	v_pk_add_f32 v[14:15], v[194:195], v[192:193]
	s_nop 0
	v_pk_add_f32 v[14:15], v[190:191], v[14:15]
	s_waitcnt lgkmcnt(5)
	v_mfma_f32_32x32x16_bf16 v[32:47], v[104:107], v[2:5], v[32:47]
	ds_read_b128 v[100:103], v234 offset:25664
	v_exp_f32_e32 v0, v83
	v_exp_f32_e32 v190, v84
	v_exp_f32_e32 v105, v85
	v_add_f32_e32 v107, v0, v190
	s_waitcnt lgkmcnt(5)
	v_mfma_f32_32x32x16_bf16 v[16:31], v[108:111], v[2:5], v[16:31]
	ds_read_b128 v[80:83], v234 offset:30272
	v_exp_f32_e32 v106, v86
	v_exp_f32_e32 v104, v87
	s_nop 0
	v_pk_add_f32 v[108:109], v[104:105], v[106:107]
	s_waitcnt lgkmcnt(5)
	v_mfma_f32_32x32x16_bf16 v[64:79], v[182:185], v[6:9], v[64:79]
	ds_read_b128 v[2:5], v234 offset:34880
	v_exp_f32_e32 v111, v88
	v_exp_f32_e32 v185, v89
	s_waitcnt lgkmcnt(5)
	v_mfma_f32_32x32x16_bf16 v[48:63], v[186:189], v[6:9], v[48:63]
	v_exp_f32_e32 v110, v90
	v_exp_f32_e32 v184, v91
	ds_read_b128 v[84:87], v234 offset:39488
	v_pk_add_f32 v[182:183], v[184:185], v[110:111]
	s_waitcnt lgkmcnt(5)
	v_mfma_f32_32x32x16_bf16 v[32:47], v[10:13], v[6:9], v[32:47]
	ds_read_b128 v[88:91], v234 offset:25696
	v_exp_f32_e32 v187, v92
	v_exp_f32_e32 v189, v93
	s_waitcnt lgkmcnt(5)
	v_mfma_f32_32x32x16_bf16 v[16:31], v[96:99], v[6:9], v[16:31]
	v_exp_f32_e32 v186, v94
	v_exp_f32_e32 v188, v95
	v_add_f32_e32 v92, v14, v15
	v_add_f32_e32 v92, v109, v92
	v_add_f32_e32 v6, v108, v92
	ds_read_b128 v[10:13], v234 offset:30304
	v_add_f32_e32 v6, v183, v6
	v_pk_add_f32 v[14:15], v[188:189], v[186:187]
	v_add_f32_e32 v6, v182, v6
	v_add_f32_e32 v6, v15, v6
	v_add_f32_e32 v182, v14, v6
	v_cvt_pk_bf16_f32 v6, v195, v193
	v_cvt_pk_bf16_f32 v7, v191, v0
	v_cvt_pk_bf16_f32 v8, v190, v105
	v_cvt_pk_bf16_f32 v9, v106, v104
	v_cvt_pk_bf16_f32 v92, v111, v185
	v_cvt_pk_bf16_f32 v93, v110, v184
	v_cvt_pk_bf16_f32 v94, v187, v189
	v_cvt_pk_bf16_f32 v95, v186, v188
	s_waitcnt lgkmcnt(5)
	v_mfma_f32_32x32x16_bf16 v[64:79], v[100:103], v[6:9], v[64:79]
	ds_read_b128 v[96:99], v234 offset:34912
	s_waitcnt lgkmcnt(5)
	v_mfma_f32_32x32x16_bf16 v[48:63], v[80:83], v[6:9], v[48:63]
	ds_read_b128 v[100:103], v234 offset:39520
	s_waitcnt lgkmcnt(5)
	v_mfma_f32_32x32x16_bf16 v[32:47], v[2:5], v[6:9], v[32:47]
	s_waitcnt lgkmcnt(4)
	v_mfma_f32_32x32x16_bf16 v[16:31], v[84:87], v[6:9], v[16:31]
	s_waitcnt lgkmcnt(3)
	v_mfma_f32_32x32x16_bf16 v[64:79], v[88:91], v[92:95], v[64:79]
	s_waitcnt lgkmcnt(2)
	v_mfma_f32_32x32x16_bf16 v[48:63], v[10:13], v[92:95], v[48:63]
	s_waitcnt lgkmcnt(1)
	v_mfma_f32_32x32x16_bf16 v[32:47], v[96:99], v[92:95], v[32:47]
	s_waitcnt lgkmcnt(0)
	v_mfma_f32_32x32x16_bf16 v[16:31], v[100:103], v[92:95], v[16:31]
.LBB0_711:
	s_mov_b32 s98, s99
	s_add_i32 s99, s99, 0xac00
	s_cmp_eq_u32 s99, 0x20400
	s_cselect_b32 s99, 0, s99
	s_cmp_eq_u32 s8, s9
	s_waitcnt lgkmcnt(0)
	s_cbranch_scc1 .Lattn2_exit
	s_mov_b32 s10, s9
	s_branch .LBB0_709
.Lattn2_stage_only:
	s_mul_i32 s11, s6, 0x6000
	s_waitcnt vmcnt(4)
	ds_write_b128 v247, v[112:115]
	buffer_load_dwordx4 v[112:115], v207, s[20:23], s11 offen
	s_add_i32 s16, s11, 0x2000
	s_waitcnt vmcnt(4)
	ds_write_b128 v248, v[116:119]
	buffer_load_dwordx4 v[116:119], v207, s[20:23], s16 offen
	s_addk_i32 s11, 0x4000
	s_waitcnt vmcnt(4)
	ds_write_b128 v249, v[120:123]
	buffer_load_dwordx4 v[120:123], v207, s[20:23], s11 offen
	s_lshl_b32 s11, s6, 7
	s_waitcnt vmcnt(4)
	ds_write_b128 v250, v[124:127] offset:25600
	buffer_load_dwordx4 v[124:127], v209, s[24:27], s11 offen
	s_add_i32 s11, s11, 0x100000
	s_waitcnt vmcnt(4)
	ds_write_b128 v251, v[128:131] offset:25600
	buffer_load_dwordx4 v[128:131], v209, s[24:27], s11 offen
	s_waitcnt lgkmcnt(0)
	s_barrier
	s_branch .LBB0_711

	.amdhsa_kernel _Z8fwd_mega6Params
		.amdhsa_group_segment_fixed_size 0
		.amdhsa_private_segment_fixed_size 0
		.amdhsa_kernarg_size 400
		.amdhsa_user_sgpr_count 2
		.amdhsa_user_sgpr_dispatch_ptr 0
		.amdhsa_user_sgpr_queue_ptr 0
		.amdhsa_user_sgpr_kernarg_segment_ptr 1
		.amdhsa_user_sgpr_dispatch_id 0
		.amdhsa_user_sgpr_kernarg_preload_length 0
		.amdhsa_user_sgpr_kernarg_preload_offset 0
		.amdhsa_user_sgpr_private_segment_size 0
		.amdhsa_uses_dynamic_stack 0
		.amdhsa_enable_private_segment 0
		.amdhsa_system_sgpr_workgroup_id_x 1
		.amdhsa_system_sgpr_workgroup_id_y 0
		.amdhsa_system_sgpr_workgroup_id_z 0
		.amdhsa_system_sgpr_workgroup_info 0
		.amdhsa_system_vgpr_workitem_id 2
		.amdhsa_next_free_vgpr 252
		.amdhsa_next_free_sgpr 100
		.amdhsa_accum_offset 252
		.amdhsa_reserve_vcc 1
		.amdhsa_float_round_mode_32 0
		.amdhsa_float_round_mode_16_64 0
		.amdhsa_float_denorm_mode_32 3
		.amdhsa_float_denorm_mode_16_64 3
		.amdhsa_dx10_clamp 1
		.amdhsa_ieee_mode 1
		.amdhsa_fp16_overflow 0
		.amdhsa_tg_split 0
		.amdhsa_exception_fp_ieee_invalid_op 0
		.amdhsa_exception_fp_denorm_src 0
		.amdhsa_exception_fp_ieee_div_zero 0
		.amdhsa_exception_fp_ieee_overflow 0
		.amdhsa_exception_fp_ieee_underflow 0
		.amdhsa_exception_fp_ieee_inexact 0
		.amdhsa_exception_int_div_zero 0
	.end_amdhsa_kernel

amdhsa.kernels:
  - .agpr_count:     0
    .args:
      - .offset:         0
        .size:           144
        .value_kind:     by_value
      - .offset:         144
        .size:           4
        .value_kind:     hidden_block_count_x
      - .offset:         148
        .size:           4
        .value_kind:     hidden_block_count_y
      - .offset:         152
        .size:           4
        .value_kind:     hidden_block_count_z
      - .offset:         156
        .size:           2
        .value_kind:     hidden_group_size_x
      - .offset:         158
        .size:           2
        .value_kind:     hidden_group_size_y
      - .offset:         160
        .size:           2
        .value_kind:     hidden_group_size_z
      - .offset:         162
        .size:           2
        .value_kind:     hidden_remainder_x
      - .offset:         164
        .size:           2
        .value_kind:     hidden_remainder_y
      - .offset:         166
        .size:           2
        .value_kind:     hidden_remainder_z
      - .offset:         184
        .size:           8
        .value_kind:     hidden_global_offset_x
      - .offset:         192
        .size:           8
        .value_kind:     hidden_global_offset_y
      - .offset:         200
        .size:           8
        .value_kind:     hidden_global_offset_z
      - .offset:         208
        .size:           2
        .value_kind:     hidden_grid_dims
      - .offset:         232
        .size:           8
        .value_kind:     hidden_multigrid_sync_arg
      - .offset:         264
        .size:           4
        .value_kind:     hidden_dynamic_lds_size
    .group_segment_fixed_size: 0
    .kernarg_segment_align: 8
    .kernarg_segment_size: 400
    .language:       OpenCL C
    .language_version:
      - 2
      - 0
    .max_flat_workgroup_size: 512
    .name:           _Z8fwd_mega6Params
    .private_segment_fixed_size: 0
    .sgpr_count:     106
    .sgpr_spill_count: 212
    .symbol:         _Z8fwd_mega6Params.kd
    .uniform_work_group_size: 1
    .uses_dynamic_stack: false
    .vgpr_count:     252
    .vgpr_spill_count: 0
    .wavefront_size: 64
